# diff fast loop: the four row-sum MFMAs issued back-to-back right behind the last PV MFMA so the exps and bf16 conversions run under them
# baseline (speedup 1.0000x reference)
.Lf_459:
	v_mov_b32_e32 v180, v128
	v_mov_b32_e32 v181, v129
	v_mov_b32_e32 v182, v130
	v_mov_b32_e32 v183, v131
	v_mfma_f32_32x32x16_bf16 v[64:79], v[176:179], v[140:143], v[64:79]
	ds_read_b64_tr_b16 v[128:129], v0 offset:24576
	ds_read_b64_tr_b16 v[130:131], v0 offset:25088
	v_exp_f32_e32 v14, v112
	v_mfma_f32_32x32x16_bf16 v[64:79], v[172:175], v[136:139], v[64:79]
	ds_read_b64_tr_b16 v[172:173], v0 offset:25600
	ds_read_b64_tr_b16 v[174:175], v0 offset:26112
	v_exp_f32_e32 v15, v96
	v_mfma_f32_32x32x16_bf16 v[64:79], v[168:171], v[132:135], v[64:79]
	ds_read_b64_tr_b16 v[168:169], v0 offset:26624
	ds_read_b64_tr_b16 v[170:171], v0 offset:27136
	v_exp_f32_e32 v96, v113
	v_mfma_f32_32x32x16_bf16 v[64:79], v[164:167], v[180:183], v[64:79]
	ds_read_b64_tr_b16 v[164:165], v0 offset:27648
	ds_read_b64_tr_b16 v[166:167], v0 offset:28160
	v_exp_f32_e32 v97, v97
	v_mfma_f32_32x32x16_bf16 v[48:63], v[160:163], v[140:143], v[48:63]
	ds_read_b64_tr_b16 v[160:161], v0 offset:28672
	ds_read_b64_tr_b16 v[162:163], v0 offset:29184
	v_exp_f32_e32 v112, v114
	v_mfma_f32_32x32x16_bf16 v[48:63], v[10:13], v[136:139], v[48:63]
	ds_read_b64_tr_b16 v[10:11], v0 offset:29696
	ds_read_b64_tr_b16 v[12:13], v0 offset:30208
	v_exp_f32_e32 v98, v98
	v_mfma_f32_32x32x16_bf16 v[48:63], v[6:9], v[132:135], v[48:63]
	ds_read_b64_tr_b16 v[6:7], v0 offset:30720
	ds_read_b64_tr_b16 v[8:9], v0 offset:31232
	v_exp_f32_e32 v113, v115
	v_mfma_f32_32x32x16_bf16 v[48:63], v[2:5], v[180:183], v[48:63]
	ds_read_b64_tr_b16 v[2:3], v0 offset:31744
	ds_read_b64_tr_b16 v[4:5], v0 offset:32256
	v_exp_f32_e32 v0, v99
	s_waitcnt lgkmcnt(14)
	v_mfma_f32_32x32x16_bf16 v[32:47], v[128:131], v[140:143], v[32:47]
	v_exp_f32_e32 v99, v116
	v_exp_f32_e32 v100, v100
	v_exp_f32_e32 v114, v117
	s_waitcnt lgkmcnt(12)
	v_mfma_f32_32x32x16_bf16 v[32:47], v[172:175], v[136:139], v[32:47]
	v_exp_f32_e32 v101, v101
	v_exp_f32_e32 v115, v118
	v_exp_f32_e32 v102, v102
	s_waitcnt lgkmcnt(10)
	v_mfma_f32_32x32x16_bf16 v[32:47], v[168:171], v[132:135], v[32:47]
	v_exp_f32_e32 v116, v119
	v_exp_f32_e32 v103, v103
	v_exp_f32_e32 v117, v120
	s_waitcnt lgkmcnt(8)
	v_mfma_f32_32x32x16_bf16 v[32:47], v[164:167], v[180:183], v[32:47]
	v_exp_f32_e32 v104, v104
	v_exp_f32_e32 v118, v121
	v_exp_f32_e32 v105, v105
	s_waitcnt lgkmcnt(6)
	v_mfma_f32_32x32x16_bf16 v[16:31], v[160:163], v[140:143], v[16:31]
	v_exp_f32_e32 v119, v122
	v_exp_f32_e32 v106, v106
	v_exp_f32_e32 v120, v123
	s_waitcnt lgkmcnt(4)
	v_mfma_f32_32x32x16_bf16 v[16:31], v[10:13], v[136:139], v[16:31]
	v_exp_f32_e32 v10, v107
	v_exp_f32_e32 v11, v124
	v_exp_f32_e32 v12, v108
	s_waitcnt lgkmcnt(2)
	v_mfma_f32_32x32x16_bf16 v[16:31], v[6:9], v[132:135], v[16:31]
	v_exp_f32_e32 v6, v125
	v_exp_f32_e32 v7, v109
	v_exp_f32_e32 v8, v126
	s_waitcnt lgkmcnt(0)
	v_mfma_f32_32x32x16_bf16 v[16:31], v[2:5], v[180:183], v[16:31]
	v_mfma_f32_16x16x32_bf16 v[84:87], v[92:95], v[140:143], v[84:87]
	v_mfma_f32_16x16x32_bf16 v[84:87], v[92:95], v[136:139], v[84:87]
	v_mfma_f32_16x16x32_bf16 v[84:87], v[92:95], v[132:135], v[84:87]
	v_mfma_f32_16x16x32_bf16 v[84:87], v[92:95], v[180:183], v[84:87]
	v_exp_f32_e32 v107, v110
	s_nop 0
	v_exp_f32_e32 v108, v127
	v_exp_f32_e32 v109, v111
	v_cvt_pk_bf16_f32 v140, v14, v96
	v_cvt_pk_bf16_f32 v143, v115, v116
	v_cvt_pk_bf16_f32 v128, v104, v105
	v_cvt_pk_bf16_f32 v141, v112, v113
	v_cvt_pk_bf16_f32 v136, v117, v118
	v_cvt_pk_bf16_f32 v137, v119, v120
	v_cvt_pk_bf16_f32 v129, v106, v10
	v_cvt_pk_bf16_f32 v132, v15, v97
	v_cvt_pk_bf16_f32 v130, v12, v7
	v_cvt_pk_bf16_f32 v138, v11, v6
	v_cvt_pk_bf16_f32 v133, v98, v0
	v_cvt_pk_bf16_f32 v142, v99, v114
	v_cvt_pk_bf16_f32 v134, v100, v101
	v_cvt_pk_bf16_f32 v135, v102, v103
	v_cvt_pk_bf16_f32 v139, v8, v108
	v_cvt_pk_bf16_f32 v131, v107, v109
	s_add_i32 s28, s28, 1
	s_add_i32 s13, s13, 1
	s_add_i32 s19, s19, 0x8000
	s_cmpk_eq_i32 s13, 0x45
	s_cbranch_scc1 .Lf_fold464
